# GLA scan item: six rounds unrolled, next round's loads issued before the current round's state update (two register sets)
# speedup vs baseline: 1.0104x; 1.0061x over previous
.LBB0_742:
	v_lshl_add_u64 v[22:23], s[48:49], 0, v[10:11]
	v_add_u32_e32 v0, s0, v2
	v_add_co_u32_e32 v16, vcc, 0xc97c000, v22
	v_lshl_add_u64 v[18:19], s[48:49], 0, v[8:9]
	v_add_u32_e32 v20, 7, v0
	v_addc_co_u32_e32 v17, vcc, 0, v23, vcc
	v_add_co_u32_e32 v30, vcc, 0xaac000, v18
	v_ashrrev_i32_e32 v21, 31, v20
	s_nop 0
	v_addc_co_u32_e32 v31, vcc, 0, v19, vcc
	v_lshlrev_b64 v[32:33], 14, v[20:21]
	v_lshlrev_b64 v[34:35], 8, v[20:21]
	global_load_dwordx2 v[44:45], v[16:17], off
	global_load_dwordx4 v[18:21], v[30:31], off
	v_add_u32_e32 v24, 9, v0
	v_add_u32_e32 v26, 10, v0
	v_add_u32_e32 v28, 11, v0
	v_ashrrev_i32_e32 v25, 31, v24
	v_ashrrev_i32_e32 v27, 31, v26
	v_ashrrev_i32_e32 v29, 31, v28
	s_mov_b32 s1, 0xc984000
	v_lshlrev_b64 v[36:37], 14, v[24:25]
	v_lshlrev_b64 v[24:25], 8, v[24:25]
	v_lshlrev_b64 v[38:39], 14, v[26:27]
	v_lshlrev_b64 v[26:27], 8, v[26:27]
	v_lshlrev_b64 v[40:41], 14, v[28:29]
	v_lshlrev_b64 v[28:29], 8, v[28:29]
	v_add_co_u32_e32 v42, vcc, s1, v22
	v_lshl_add_u64 v[46:47], v[4:5], 0, v[32:33]
	v_lshl_add_u64 v[32:33], v[6:7], 0, v[34:35]
	v_lshl_add_u64 v[48:49], v[4:5], 0, v[36:37]
	v_lshl_add_u64 v[34:35], v[6:7], 0, v[24:25]
	v_lshl_add_u64 v[50:51], v[4:5], 0, v[38:39]
	v_lshl_add_u64 v[36:37], v[6:7], 0, v[26:27]
	v_lshl_add_u64 v[38:39], v[6:7], 0, v[28:29]
	v_addc_co_u32_e32 v43, vcc, 0, v23, vcc
	v_lshl_add_u64 v[52:53], v[4:5], 0, v[40:41]
	global_load_dwordx2 v[54:55], v[46:47], off
	global_load_dwordx2 v[56:57], v[42:43], off
	global_load_dwordx2 v[58:59], v[48:49], off
	global_load_dwordx2 v[60:61], v[50:51], off
	global_load_dwordx2 v[62:63], v[52:53], off
	global_load_dwordx4 v[22:25], v[32:33], off
	global_load_dwordx4 v[26:29], v[30:31], off offset:512
	s_nop 0
	global_load_dwordx4 v[30:33], v[34:35], off
	s_nop 0
	global_load_dwordx4 v[34:37], v[36:37], off
	s_nop 0
	global_load_dwordx4 v[38:41], v[38:39], off
	s_add_i32 s0, s0, 6
	s_mov_b64 s[6:7], 0x600
	v_lshl_add_u64 v[8:9], v[8:9], 0, s[6:7]
	v_lshl_add_u64 v[10:11], v[10:11], 0, s[8:9]
	v_lshl_add_u64 v[106:107], s[48:49], 0, v[10:11]
	v_add_u32_e32 v84, s0, v2
	v_add_co_u32_e32 v100, vcc, 0xc97c000, v106
	v_lshl_add_u64 v[102:103], s[48:49], 0, v[8:9]
	v_add_u32_e32 v104, 7, v84
	v_addc_co_u32_e32 v101, vcc, 0, v107, vcc
	v_add_co_u32_e32 v114, vcc, 0xaac000, v102
	v_ashrrev_i32_e32 v105, 31, v104
	s_nop 0
	v_addc_co_u32_e32 v115, vcc, 0, v103, vcc
	v_lshlrev_b64 v[116:117], 14, v[104:105]
	v_lshlrev_b64 v[118:119], 8, v[104:105]
	global_load_dwordx2 v[128:129], v[100:101], off
	global_load_dwordx4 v[102:105], v[114:115], off
	v_add_u32_e32 v108, 9, v84
	v_add_u32_e32 v110, 10, v84
	v_add_u32_e32 v112, 11, v84
	v_ashrrev_i32_e32 v109, 31, v108
	v_ashrrev_i32_e32 v111, 31, v110
	v_ashrrev_i32_e32 v113, 31, v112
	s_mov_b32 s1, 0xc984000
	v_lshlrev_b64 v[120:121], 14, v[108:109]
	v_lshlrev_b64 v[108:109], 8, v[108:109]
	v_lshlrev_b64 v[122:123], 14, v[110:111]
	v_lshlrev_b64 v[110:111], 8, v[110:111]
	v_lshlrev_b64 v[124:125], 14, v[112:113]
	v_lshlrev_b64 v[112:113], 8, v[112:113]
	v_add_co_u32_e32 v126, vcc, s1, v106
	v_lshl_add_u64 v[130:131], v[4:5], 0, v[116:117]
	v_lshl_add_u64 v[116:117], v[6:7], 0, v[118:119]
	v_lshl_add_u64 v[132:133], v[4:5], 0, v[120:121]
	v_lshl_add_u64 v[118:119], v[6:7], 0, v[108:109]
	v_lshl_add_u64 v[134:135], v[4:5], 0, v[122:123]
	v_lshl_add_u64 v[120:121], v[6:7], 0, v[110:111]
	v_lshl_add_u64 v[122:123], v[6:7], 0, v[112:113]
	v_addc_co_u32_e32 v127, vcc, 0, v107, vcc
	v_lshl_add_u64 v[136:137], v[4:5], 0, v[124:125]
	global_load_dwordx2 v[138:139], v[130:131], off
	global_load_dwordx2 v[140:141], v[126:127], off
	global_load_dwordx2 v[142:143], v[132:133], off
	global_load_dwordx2 v[144:145], v[134:135], off
	global_load_dwordx2 v[146:147], v[136:137], off
	global_load_dwordx4 v[106:109], v[116:117], off
	global_load_dwordx4 v[110:113], v[114:115], off offset:512
	s_nop 0
	global_load_dwordx4 v[114:117], v[118:119], off
	s_nop 0
	global_load_dwordx4 v[118:121], v[120:121], off
	s_nop 0
	global_load_dwordx4 v[122:125], v[122:123], off
	s_add_i32 s0, s0, 6
	s_mov_b64 s[6:7], 0x600
	v_lshl_add_u64 v[8:9], v[8:9], 0, s[6:7]
	v_lshl_add_u64 v[10:11], v[10:11], 0, s[8:9]
	v_cvt_pk_bf16_f32 v64, v14, v15
	v_cvt_pk_bf16_f32 v65, v12, v13
	global_store_dwordx2 v[16:17], v[64:65], off
	s_waitcnt vmcnt(24)
	v_lshlrev_b32_e32 v16, 16, v44
	v_and_b32_e32 v17, 0xffff0000, v44
	v_lshlrev_b32_e32 v44, 16, v45
	v_and_b32_e32 v45, 0xffff0000, v45
	s_waitcnt vmcnt(23)
	v_pk_fma_f32 v[14:15], v[14:15], v[18:19], v[16:17]
	v_pk_fma_f32 v[12:13], v[12:13], v[20:21], v[44:45]
	v_cvt_pk_bf16_f32 v20, v14, v15
	v_cvt_pk_bf16_f32 v21, v12, v13
	global_store_dwordx2 v[46:47], v[20:21], off
	s_waitcnt vmcnt(23)
	v_lshlrev_b32_e32 v16, 16, v54
	v_and_b32_e32 v17, 0xffff0000, v54
	v_lshlrev_b32_e32 v18, 16, v55
	v_and_b32_e32 v19, 0xffff0000, v55
	s_waitcnt vmcnt(22)
	v_and_b32_e32 v45, 0xffff0000, v56
	v_lshlrev_b32_e32 v44, 16, v56
	v_and_b32_e32 v69, 0xffff0000, v57
	v_lshlrev_b32_e32 v68, 16, v57
	s_waitcnt vmcnt(18)
	v_pk_fma_f32 v[14:15], v[14:15], v[22:23], v[16:17]
	v_pk_fma_f32 v[12:13], v[12:13], v[24:25], v[18:19]
	v_and_b32_e32 v55, 0xffff0000, v58
	v_lshlrev_b32_e32 v54, 16, v58
	v_and_b32_e32 v57, 0xffff0000, v59
	v_lshlrev_b32_e32 v56, 16, v59
	v_cvt_pk_bf16_f32 v16, v14, v15
	s_waitcnt vmcnt(17)
	v_pk_fma_f32 v[14:15], v[14:15], v[26:27], v[44:45]
	v_cvt_pk_bf16_f32 v17, v12, v13
	v_pk_fma_f32 v[12:13], v[12:13], v[28:29], v[68:69]
	v_and_b32_e32 v65, 0xffff0000, v60
	v_lshlrev_b32_e32 v64, 16, v60
	v_and_b32_e32 v59, 0xffff0000, v61
	v_lshlrev_b32_e32 v58, 16, v61
	v_cvt_pk_bf16_f32 v18, v14, v15
	s_waitcnt vmcnt(16)
	v_pk_fma_f32 v[14:15], v[14:15], v[30:31], v[54:55]
	v_cvt_pk_bf16_f32 v19, v12, v13
	v_pk_fma_f32 v[12:13], v[12:13], v[32:33], v[56:57]
	v_and_b32_e32 v67, 0xffff0000, v62
	v_lshlrev_b32_e32 v66, 16, v62
	v_and_b32_e32 v61, 0xffff0000, v63
	v_lshlrev_b32_e32 v60, 16, v63
	global_store_dwordx2 v[42:43], v[16:17], off
	v_cvt_pk_bf16_f32 v16, v14, v15
	s_waitcnt vmcnt(16)
	v_pk_fma_f32 v[14:15], v[14:15], v[34:35], v[64:65]
	v_cvt_pk_bf16_f32 v17, v12, v13
	v_pk_fma_f32 v[12:13], v[12:13], v[36:37], v[58:59]
	global_store_dwordx2 v[48:49], v[18:19], off
	v_cvt_pk_bf16_f32 v18, v14, v15
	s_waitcnt vmcnt(16)
	v_pk_fma_f32 v[14:15], v[14:15], v[38:39], v[66:67]
	v_cvt_pk_bf16_f32 v19, v12, v13
	v_pk_fma_f32 v[12:13], v[12:13], v[40:41], v[60:61]
	global_store_dwordx2 v[50:51], v[16:17], off
	global_store_dwordx2 v[52:53], v[18:19], off
	v_lshl_add_u64 v[22:23], s[48:49], 0, v[10:11]
	v_add_u32_e32 v0, s0, v2
	v_add_co_u32_e32 v16, vcc, 0xc97c000, v22
	v_lshl_add_u64 v[18:19], s[48:49], 0, v[8:9]
	v_add_u32_e32 v20, 7, v0
	v_addc_co_u32_e32 v17, vcc, 0, v23, vcc
	v_add_co_u32_e32 v30, vcc, 0xaac000, v18
	v_ashrrev_i32_e32 v21, 31, v20
	s_nop 0
	v_addc_co_u32_e32 v31, vcc, 0, v19, vcc
	v_lshlrev_b64 v[32:33], 14, v[20:21]
	v_lshlrev_b64 v[34:35], 8, v[20:21]
	global_load_dwordx2 v[44:45], v[16:17], off
	global_load_dwordx4 v[18:21], v[30:31], off
	v_add_u32_e32 v24, 9, v0
	v_add_u32_e32 v26, 10, v0
	v_add_u32_e32 v28, 11, v0
	v_ashrrev_i32_e32 v25, 31, v24
	v_ashrrev_i32_e32 v27, 31, v26
	v_ashrrev_i32_e32 v29, 31, v28
	s_mov_b32 s1, 0xc984000
	v_lshlrev_b64 v[36:37], 14, v[24:25]
	v_lshlrev_b64 v[24:25], 8, v[24:25]
	v_lshlrev_b64 v[38:39], 14, v[26:27]
	v_lshlrev_b64 v[26:27], 8, v[26:27]
	v_lshlrev_b64 v[40:41], 14, v[28:29]
	v_lshlrev_b64 v[28:29], 8, v[28:29]
	v_add_co_u32_e32 v42, vcc, s1, v22
	v_lshl_add_u64 v[46:47], v[4:5], 0, v[32:33]
	v_lshl_add_u64 v[32:33], v[6:7], 0, v[34:35]
	v_lshl_add_u64 v[48:49], v[4:5], 0, v[36:37]
	v_lshl_add_u64 v[34:35], v[6:7], 0, v[24:25]
	v_lshl_add_u64 v[50:51], v[4:5], 0, v[38:39]
	v_lshl_add_u64 v[36:37], v[6:7], 0, v[26:27]
	v_lshl_add_u64 v[38:39], v[6:7], 0, v[28:29]
	v_addc_co_u32_e32 v43, vcc, 0, v23, vcc
	v_lshl_add_u64 v[52:53], v[4:5], 0, v[40:41]
	global_load_dwordx2 v[54:55], v[46:47], off
	global_load_dwordx2 v[56:57], v[42:43], off
	global_load_dwordx2 v[58:59], v[48:49], off
	global_load_dwordx2 v[60:61], v[50:51], off
	global_load_dwordx2 v[62:63], v[52:53], off
	global_load_dwordx4 v[22:25], v[32:33], off
	global_load_dwordx4 v[26:29], v[30:31], off offset:512
	s_nop 0
	global_load_dwordx4 v[30:33], v[34:35], off
	s_nop 0
	global_load_dwordx4 v[34:37], v[36:37], off
	s_nop 0
	global_load_dwordx4 v[38:41], v[38:39], off
	s_add_i32 s0, s0, 6
	s_mov_b64 s[6:7], 0x600
	v_lshl_add_u64 v[8:9], v[8:9], 0, s[6:7]
	v_lshl_add_u64 v[10:11], v[10:11], 0, s[8:9]
	v_cvt_pk_bf16_f32 v148, v14, v15
	v_cvt_pk_bf16_f32 v149, v12, v13
	global_store_dwordx2 v[100:101], v[148:149], off
	s_waitcnt vmcnt(24)
	v_lshlrev_b32_e32 v100, 16, v128
	v_and_b32_e32 v101, 0xffff0000, v128
	v_lshlrev_b32_e32 v128, 16, v129
	v_and_b32_e32 v129, 0xffff0000, v129
	s_waitcnt vmcnt(23)
	v_pk_fma_f32 v[14:15], v[14:15], v[102:103], v[100:101]
	v_pk_fma_f32 v[12:13], v[12:13], v[104:105], v[128:129]
	v_cvt_pk_bf16_f32 v104, v14, v15
	v_cvt_pk_bf16_f32 v105, v12, v13
	global_store_dwordx2 v[130:131], v[104:105], off
	s_waitcnt vmcnt(23)
	v_lshlrev_b32_e32 v100, 16, v138
	v_and_b32_e32 v101, 0xffff0000, v138
	v_lshlrev_b32_e32 v102, 16, v139
	v_and_b32_e32 v103, 0xffff0000, v139
	s_waitcnt vmcnt(22)
	v_and_b32_e32 v129, 0xffff0000, v140
	v_lshlrev_b32_e32 v128, 16, v140
	v_and_b32_e32 v153, 0xffff0000, v141
	v_lshlrev_b32_e32 v152, 16, v141
	s_waitcnt vmcnt(18)
	v_pk_fma_f32 v[14:15], v[14:15], v[106:107], v[100:101]
	v_pk_fma_f32 v[12:13], v[12:13], v[108:109], v[102:103]
	v_and_b32_e32 v139, 0xffff0000, v142
	v_lshlrev_b32_e32 v138, 16, v142
	v_and_b32_e32 v141, 0xffff0000, v143
	v_lshlrev_b32_e32 v140, 16, v143
	v_cvt_pk_bf16_f32 v100, v14, v15
	s_waitcnt vmcnt(17)
	v_pk_fma_f32 v[14:15], v[14:15], v[110:111], v[128:129]
	v_cvt_pk_bf16_f32 v101, v12, v13
	v_pk_fma_f32 v[12:13], v[12:13], v[112:113], v[152:153]
	v_and_b32_e32 v149, 0xffff0000, v144
	v_lshlrev_b32_e32 v148, 16, v144
	v_and_b32_e32 v143, 0xffff0000, v145
	v_lshlrev_b32_e32 v142, 16, v145
	v_cvt_pk_bf16_f32 v102, v14, v15
	s_waitcnt vmcnt(16)
	v_pk_fma_f32 v[14:15], v[14:15], v[114:115], v[138:139]
	v_cvt_pk_bf16_f32 v103, v12, v13
	v_pk_fma_f32 v[12:13], v[12:13], v[116:117], v[140:141]
	v_and_b32_e32 v151, 0xffff0000, v146
	v_lshlrev_b32_e32 v150, 16, v146
	v_and_b32_e32 v145, 0xffff0000, v147
	v_lshlrev_b32_e32 v144, 16, v147
	global_store_dwordx2 v[126:127], v[100:101], off
	v_cvt_pk_bf16_f32 v100, v14, v15
	s_waitcnt vmcnt(16)
	v_pk_fma_f32 v[14:15], v[14:15], v[118:119], v[148:149]
	v_cvt_pk_bf16_f32 v101, v12, v13
	v_pk_fma_f32 v[12:13], v[12:13], v[120:121], v[142:143]
	global_store_dwordx2 v[132:133], v[102:103], off
	v_cvt_pk_bf16_f32 v102, v14, v15
	s_waitcnt vmcnt(16)
	v_pk_fma_f32 v[14:15], v[14:15], v[122:123], v[150:151]
	v_cvt_pk_bf16_f32 v103, v12, v13
	v_pk_fma_f32 v[12:13], v[12:13], v[124:125], v[144:145]
	global_store_dwordx2 v[134:135], v[100:101], off
	global_store_dwordx2 v[136:137], v[102:103], off
	v_lshl_add_u64 v[106:107], s[48:49], 0, v[10:11]
	v_add_u32_e32 v84, s0, v2
	v_add_co_u32_e32 v100, vcc, 0xc97c000, v106
	v_lshl_add_u64 v[102:103], s[48:49], 0, v[8:9]
	v_add_u32_e32 v104, 7, v84
	v_addc_co_u32_e32 v101, vcc, 0, v107, vcc
	v_add_co_u32_e32 v114, vcc, 0xaac000, v102
	v_ashrrev_i32_e32 v105, 31, v104
	s_nop 0
	v_addc_co_u32_e32 v115, vcc, 0, v103, vcc
	v_lshlrev_b64 v[116:117], 14, v[104:105]
	v_lshlrev_b64 v[118:119], 8, v[104:105]
	global_load_dwordx2 v[128:129], v[100:101], off
	global_load_dwordx4 v[102:105], v[114:115], off
	v_add_u32_e32 v108, 9, v84
	v_add_u32_e32 v110, 10, v84
	v_add_u32_e32 v112, 11, v84
	v_ashrrev_i32_e32 v109, 31, v108
	v_ashrrev_i32_e32 v111, 31, v110
	v_ashrrev_i32_e32 v113, 31, v112
	s_mov_b32 s1, 0xc984000
	v_lshlrev_b64 v[120:121], 14, v[108:109]
	v_lshlrev_b64 v[108:109], 8, v[108:109]
	v_lshlrev_b64 v[122:123], 14, v[110:111]
	v_lshlrev_b64 v[110:111], 8, v[110:111]
	v_lshlrev_b64 v[124:125], 14, v[112:113]
	v_lshlrev_b64 v[112:113], 8, v[112:113]
	v_add_co_u32_e32 v126, vcc, s1, v106
	v_lshl_add_u64 v[130:131], v[4:5], 0, v[116:117]
	v_lshl_add_u64 v[116:117], v[6:7], 0, v[118:119]
	v_lshl_add_u64 v[132:133], v[4:5], 0, v[120:121]
	v_lshl_add_u64 v[118:119], v[6:7], 0, v[108:109]
	v_lshl_add_u64 v[134:135], v[4:5], 0, v[122:123]
	v_lshl_add_u64 v[120:121], v[6:7], 0, v[110:111]
	v_lshl_add_u64 v[122:123], v[6:7], 0, v[112:113]
	v_addc_co_u32_e32 v127, vcc, 0, v107, vcc
	v_lshl_add_u64 v[136:137], v[4:5], 0, v[124:125]
	global_load_dwordx2 v[138:139], v[130:131], off
	global_load_dwordx2 v[140:141], v[126:127], off
	global_load_dwordx2 v[142:143], v[132:133], off
	global_load_dwordx2 v[144:145], v[134:135], off
	global_load_dwordx2 v[146:147], v[136:137], off
	global_load_dwordx4 v[106:109], v[116:117], off
	global_load_dwordx4 v[110:113], v[114:115], off offset:512
	s_nop 0
	global_load_dwordx4 v[114:117], v[118:119], off
	s_nop 0
	global_load_dwordx4 v[118:121], v[120:121], off
	s_nop 0
	global_load_dwordx4 v[122:125], v[122:123], off
	s_add_i32 s0, s0, 6
	s_mov_b64 s[6:7], 0x600
	v_lshl_add_u64 v[8:9], v[8:9], 0, s[6:7]
	v_lshl_add_u64 v[10:11], v[10:11], 0, s[8:9]
	v_cvt_pk_bf16_f32 v64, v14, v15
	v_cvt_pk_bf16_f32 v65, v12, v13
	global_store_dwordx2 v[16:17], v[64:65], off
	s_waitcnt vmcnt(24)
	v_lshlrev_b32_e32 v16, 16, v44
	v_and_b32_e32 v17, 0xffff0000, v44
	v_lshlrev_b32_e32 v44, 16, v45
	v_and_b32_e32 v45, 0xffff0000, v45
	s_waitcnt vmcnt(23)
	v_pk_fma_f32 v[14:15], v[14:15], v[18:19], v[16:17]
	v_pk_fma_f32 v[12:13], v[12:13], v[20:21], v[44:45]
	v_cvt_pk_bf16_f32 v20, v14, v15
	v_cvt_pk_bf16_f32 v21, v12, v13
	global_store_dwordx2 v[46:47], v[20:21], off
	s_waitcnt vmcnt(23)
	v_lshlrev_b32_e32 v16, 16, v54
	v_and_b32_e32 v17, 0xffff0000, v54
	v_lshlrev_b32_e32 v18, 16, v55
	v_and_b32_e32 v19, 0xffff0000, v55
	s_waitcnt vmcnt(22)
	v_and_b32_e32 v45, 0xffff0000, v56
	v_lshlrev_b32_e32 v44, 16, v56
	v_and_b32_e32 v69, 0xffff0000, v57
	v_lshlrev_b32_e32 v68, 16, v57
	s_waitcnt vmcnt(18)
	v_pk_fma_f32 v[14:15], v[14:15], v[22:23], v[16:17]
	v_pk_fma_f32 v[12:13], v[12:13], v[24:25], v[18:19]
	v_and_b32_e32 v55, 0xffff0000, v58
	v_lshlrev_b32_e32 v54, 16, v58
	v_and_b32_e32 v57, 0xffff0000, v59
	v_lshlrev_b32_e32 v56, 16, v59
	v_cvt_pk_bf16_f32 v16, v14, v15
	s_waitcnt vmcnt(17)
	v_pk_fma_f32 v[14:15], v[14:15], v[26:27], v[44:45]
	v_cvt_pk_bf16_f32 v17, v12, v13
	v_pk_fma_f32 v[12:13], v[12:13], v[28:29], v[68:69]
	v_and_b32_e32 v65, 0xffff0000, v60
	v_lshlrev_b32_e32 v64, 16, v60
	v_and_b32_e32 v59, 0xffff0000, v61
	v_lshlrev_b32_e32 v58, 16, v61
	v_cvt_pk_bf16_f32 v18, v14, v15
	s_waitcnt vmcnt(16)
	v_pk_fma_f32 v[14:15], v[14:15], v[30:31], v[54:55]
	v_cvt_pk_bf16_f32 v19, v12, v13
	v_pk_fma_f32 v[12:13], v[12:13], v[32:33], v[56:57]
	v_and_b32_e32 v67, 0xffff0000, v62
	v_lshlrev_b32_e32 v66, 16, v62
	v_and_b32_e32 v61, 0xffff0000, v63
	v_lshlrev_b32_e32 v60, 16, v63
	global_store_dwordx2 v[42:43], v[16:17], off
	v_cvt_pk_bf16_f32 v16, v14, v15
	s_waitcnt vmcnt(16)
	v_pk_fma_f32 v[14:15], v[14:15], v[34:35], v[64:65]
	v_cvt_pk_bf16_f32 v17, v12, v13
	v_pk_fma_f32 v[12:13], v[12:13], v[36:37], v[58:59]
	global_store_dwordx2 v[48:49], v[18:19], off
	v_cvt_pk_bf16_f32 v18, v14, v15
	s_waitcnt vmcnt(16)
	v_pk_fma_f32 v[14:15], v[14:15], v[38:39], v[66:67]
	v_cvt_pk_bf16_f32 v19, v12, v13
	v_pk_fma_f32 v[12:13], v[12:13], v[40:41], v[60:61]
	global_store_dwordx2 v[50:51], v[16:17], off
	global_store_dwordx2 v[52:53], v[18:19], off
	v_lshl_add_u64 v[22:23], s[48:49], 0, v[10:11]
	v_add_u32_e32 v0, s0, v2
	v_add_co_u32_e32 v16, vcc, 0xc97c000, v22
	v_lshl_add_u64 v[18:19], s[48:49], 0, v[8:9]
	v_add_u32_e32 v20, 7, v0
	v_addc_co_u32_e32 v17, vcc, 0, v23, vcc
	v_add_co_u32_e32 v30, vcc, 0xaac000, v18
	v_ashrrev_i32_e32 v21, 31, v20
	s_nop 0
	v_addc_co_u32_e32 v31, vcc, 0, v19, vcc
	v_lshlrev_b64 v[32:33], 14, v[20:21]
	v_lshlrev_b64 v[34:35], 8, v[20:21]
	global_load_dwordx2 v[44:45], v[16:17], off
	global_load_dwordx4 v[18:21], v[30:31], off
	v_add_u32_e32 v24, 9, v0
	v_add_u32_e32 v26, 10, v0
	v_add_u32_e32 v28, 11, v0
	v_ashrrev_i32_e32 v25, 31, v24
	v_ashrrev_i32_e32 v27, 31, v26
	v_ashrrev_i32_e32 v29, 31, v28
	s_mov_b32 s1, 0xc984000
	v_lshlrev_b64 v[36:37], 14, v[24:25]
	v_lshlrev_b64 v[24:25], 8, v[24:25]
	v_lshlrev_b64 v[38:39], 14, v[26:27]
	v_lshlrev_b64 v[26:27], 8, v[26:27]
	v_lshlrev_b64 v[40:41], 14, v[28:29]
	v_lshlrev_b64 v[28:29], 8, v[28:29]
	v_add_co_u32_e32 v42, vcc, s1, v22
	v_lshl_add_u64 v[46:47], v[4:5], 0, v[32:33]
	v_lshl_add_u64 v[32:33], v[6:7], 0, v[34:35]
	v_lshl_add_u64 v[48:49], v[4:5], 0, v[36:37]
	v_lshl_add_u64 v[34:35], v[6:7], 0, v[24:25]
	v_lshl_add_u64 v[50:51], v[4:5], 0, v[38:39]
	v_lshl_add_u64 v[36:37], v[6:7], 0, v[26:27]
	v_lshl_add_u64 v[38:39], v[6:7], 0, v[28:29]
	v_addc_co_u32_e32 v43, vcc, 0, v23, vcc
	v_lshl_add_u64 v[52:53], v[4:5], 0, v[40:41]
	global_load_dwordx2 v[54:55], v[46:47], off
	global_load_dwordx2 v[56:57], v[42:43], off
	global_load_dwordx2 v[58:59], v[48:49], off
	global_load_dwordx2 v[60:61], v[50:51], off
	global_load_dwordx2 v[62:63], v[52:53], off
	global_load_dwordx4 v[22:25], v[32:33], off
	global_load_dwordx4 v[26:29], v[30:31], off offset:512
	s_nop 0
	global_load_dwordx4 v[30:33], v[34:35], off
	s_nop 0
	global_load_dwordx4 v[34:37], v[36:37], off
	s_nop 0
	global_load_dwordx4 v[38:41], v[38:39], off
	s_add_i32 s0, s0, 6
	s_mov_b64 s[6:7], 0x600
	v_lshl_add_u64 v[8:9], v[8:9], 0, s[6:7]
	v_lshl_add_u64 v[10:11], v[10:11], 0, s[8:9]
	v_cvt_pk_bf16_f32 v148, v14, v15
	v_cvt_pk_bf16_f32 v149, v12, v13
	global_store_dwordx2 v[100:101], v[148:149], off
	s_waitcnt vmcnt(24)
	v_lshlrev_b32_e32 v100, 16, v128
	v_and_b32_e32 v101, 0xffff0000, v128
	v_lshlrev_b32_e32 v128, 16, v129
	v_and_b32_e32 v129, 0xffff0000, v129
	s_waitcnt vmcnt(23)
	v_pk_fma_f32 v[14:15], v[14:15], v[102:103], v[100:101]
	v_pk_fma_f32 v[12:13], v[12:13], v[104:105], v[128:129]
	v_cvt_pk_bf16_f32 v104, v14, v15
	v_cvt_pk_bf16_f32 v105, v12, v13
	global_store_dwordx2 v[130:131], v[104:105], off
	s_waitcnt vmcnt(23)
	v_lshlrev_b32_e32 v100, 16, v138
	v_and_b32_e32 v101, 0xffff0000, v138
	v_lshlrev_b32_e32 v102, 16, v139
	v_and_b32_e32 v103, 0xffff0000, v139
	s_waitcnt vmcnt(22)
	v_and_b32_e32 v129, 0xffff0000, v140
	v_lshlrev_b32_e32 v128, 16, v140
	v_and_b32_e32 v153, 0xffff0000, v141
	v_lshlrev_b32_e32 v152, 16, v141
	s_waitcnt vmcnt(18)
	v_pk_fma_f32 v[14:15], v[14:15], v[106:107], v[100:101]
	v_pk_fma_f32 v[12:13], v[12:13], v[108:109], v[102:103]
	v_and_b32_e32 v139, 0xffff0000, v142
	v_lshlrev_b32_e32 v138, 16, v142
	v_and_b32_e32 v141, 0xffff0000, v143
	v_lshlrev_b32_e32 v140, 16, v143
	v_cvt_pk_bf16_f32 v100, v14, v15
	s_waitcnt vmcnt(17)
	v_pk_fma_f32 v[14:15], v[14:15], v[110:111], v[128:129]
	v_cvt_pk_bf16_f32 v101, v12, v13
	v_pk_fma_f32 v[12:13], v[12:13], v[112:113], v[152:153]
	v_and_b32_e32 v149, 0xffff0000, v144
	v_lshlrev_b32_e32 v148, 16, v144
	v_and_b32_e32 v143, 0xffff0000, v145
	v_lshlrev_b32_e32 v142, 16, v145
	v_cvt_pk_bf16_f32 v102, v14, v15
	s_waitcnt vmcnt(16)
	v_pk_fma_f32 v[14:15], v[14:15], v[114:115], v[138:139]
	v_cvt_pk_bf16_f32 v103, v12, v13
	v_pk_fma_f32 v[12:13], v[12:13], v[116:117], v[140:141]
	v_and_b32_e32 v151, 0xffff0000, v146
	v_lshlrev_b32_e32 v150, 16, v146
	v_and_b32_e32 v145, 0xffff0000, v147
	v_lshlrev_b32_e32 v144, 16, v147
	global_store_dwordx2 v[126:127], v[100:101], off
	v_cvt_pk_bf16_f32 v100, v14, v15
	s_waitcnt vmcnt(16)
	v_pk_fma_f32 v[14:15], v[14:15], v[118:119], v[148:149]
	v_cvt_pk_bf16_f32 v101, v12, v13
	v_pk_fma_f32 v[12:13], v[12:13], v[120:121], v[142:143]
	global_store_dwordx2 v[132:133], v[102:103], off
	v_cvt_pk_bf16_f32 v102, v14, v15
	s_waitcnt vmcnt(16)
	v_pk_fma_f32 v[14:15], v[14:15], v[122:123], v[150:151]
	v_cvt_pk_bf16_f32 v103, v12, v13
	v_pk_fma_f32 v[12:13], v[12:13], v[124:125], v[144:145]
	global_store_dwordx2 v[134:135], v[100:101], off
	global_store_dwordx2 v[136:137], v[102:103], off
	v_lshl_add_u64 v[106:107], s[48:49], 0, v[10:11]
	v_add_u32_e32 v84, s0, v2
	v_add_co_u32_e32 v100, vcc, 0xc97c000, v106
	v_lshl_add_u64 v[102:103], s[48:49], 0, v[8:9]
	v_add_u32_e32 v104, 7, v84
	v_addc_co_u32_e32 v101, vcc, 0, v107, vcc
	v_add_co_u32_e32 v114, vcc, 0xaac000, v102
	v_ashrrev_i32_e32 v105, 31, v104
	s_nop 0
	v_addc_co_u32_e32 v115, vcc, 0, v103, vcc
	v_lshlrev_b64 v[116:117], 14, v[104:105]
	v_lshlrev_b64 v[118:119], 8, v[104:105]
	global_load_dwordx2 v[128:129], v[100:101], off
	global_load_dwordx4 v[102:105], v[114:115], off
	v_add_u32_e32 v108, 9, v84
	v_add_u32_e32 v110, 10, v84
	v_add_u32_e32 v112, 11, v84
	v_ashrrev_i32_e32 v109, 31, v108
	v_ashrrev_i32_e32 v111, 31, v110
	v_ashrrev_i32_e32 v113, 31, v112
	s_mov_b32 s1, 0xc984000
	v_lshlrev_b64 v[120:121], 14, v[108:109]
	v_lshlrev_b64 v[108:109], 8, v[108:109]
	v_lshlrev_b64 v[122:123], 14, v[110:111]
	v_lshlrev_b64 v[110:111], 8, v[110:111]
	v_lshlrev_b64 v[124:125], 14, v[112:113]
	v_lshlrev_b64 v[112:113], 8, v[112:113]
	v_add_co_u32_e32 v126, vcc, s1, v106
	v_lshl_add_u64 v[130:131], v[4:5], 0, v[116:117]
	v_lshl_add_u64 v[116:117], v[6:7], 0, v[118:119]
	v_lshl_add_u64 v[132:133], v[4:5], 0, v[120:121]
	v_lshl_add_u64 v[118:119], v[6:7], 0, v[108:109]
	v_lshl_add_u64 v[134:135], v[4:5], 0, v[122:123]
	v_lshl_add_u64 v[120:121], v[6:7], 0, v[110:111]
	v_lshl_add_u64 v[122:123], v[6:7], 0, v[112:113]
	v_addc_co_u32_e32 v127, vcc, 0, v107, vcc
	v_lshl_add_u64 v[136:137], v[4:5], 0, v[124:125]
	global_load_dwordx2 v[138:139], v[130:131], off
	global_load_dwordx2 v[140:141], v[126:127], off
	global_load_dwordx2 v[142:143], v[132:133], off
	global_load_dwordx2 v[144:145], v[134:135], off
	global_load_dwordx2 v[146:147], v[136:137], off
	global_load_dwordx4 v[106:109], v[116:117], off
	global_load_dwordx4 v[110:113], v[114:115], off offset:512
	s_nop 0
	global_load_dwordx4 v[114:117], v[118:119], off
	s_nop 0
	global_load_dwordx4 v[118:121], v[120:121], off
	s_nop 0
	global_load_dwordx4 v[122:125], v[122:123], off
	s_add_i32 s0, s0, 6
	s_mov_b64 s[6:7], 0x600
	v_lshl_add_u64 v[8:9], v[8:9], 0, s[6:7]
	v_lshl_add_u64 v[10:11], v[10:11], 0, s[8:9]
	v_cvt_pk_bf16_f32 v64, v14, v15
	v_cvt_pk_bf16_f32 v65, v12, v13
	global_store_dwordx2 v[16:17], v[64:65], off
	s_waitcnt vmcnt(24)
	v_lshlrev_b32_e32 v16, 16, v44
	v_and_b32_e32 v17, 0xffff0000, v44
	v_lshlrev_b32_e32 v44, 16, v45
	v_and_b32_e32 v45, 0xffff0000, v45
	s_waitcnt vmcnt(23)
	v_pk_fma_f32 v[14:15], v[14:15], v[18:19], v[16:17]
	v_pk_fma_f32 v[12:13], v[12:13], v[20:21], v[44:45]
	v_cvt_pk_bf16_f32 v20, v14, v15
	v_cvt_pk_bf16_f32 v21, v12, v13
	global_store_dwordx2 v[46:47], v[20:21], off
	s_waitcnt vmcnt(23)
	v_lshlrev_b32_e32 v16, 16, v54
	v_and_b32_e32 v17, 0xffff0000, v54
	v_lshlrev_b32_e32 v18, 16, v55
	v_and_b32_e32 v19, 0xffff0000, v55
	s_waitcnt vmcnt(22)
	v_and_b32_e32 v45, 0xffff0000, v56
	v_lshlrev_b32_e32 v44, 16, v56
	v_and_b32_e32 v69, 0xffff0000, v57
	v_lshlrev_b32_e32 v68, 16, v57
	s_waitcnt vmcnt(18)
	v_pk_fma_f32 v[14:15], v[14:15], v[22:23], v[16:17]
	v_pk_fma_f32 v[12:13], v[12:13], v[24:25], v[18:19]
	v_and_b32_e32 v55, 0xffff0000, v58
	v_lshlrev_b32_e32 v54, 16, v58
	v_and_b32_e32 v57, 0xffff0000, v59
	v_lshlrev_b32_e32 v56, 16, v59
	v_cvt_pk_bf16_f32 v16, v14, v15
	s_waitcnt vmcnt(17)
	v_pk_fma_f32 v[14:15], v[14:15], v[26:27], v[44:45]
	v_cvt_pk_bf16_f32 v17, v12, v13
	v_pk_fma_f32 v[12:13], v[12:13], v[28:29], v[68:69]
	v_and_b32_e32 v65, 0xffff0000, v60
	v_lshlrev_b32_e32 v64, 16, v60
	v_and_b32_e32 v59, 0xffff0000, v61
	v_lshlrev_b32_e32 v58, 16, v61
	v_cvt_pk_bf16_f32 v18, v14, v15
	s_waitcnt vmcnt(16)
	v_pk_fma_f32 v[14:15], v[14:15], v[30:31], v[54:55]
	v_cvt_pk_bf16_f32 v19, v12, v13
	v_pk_fma_f32 v[12:13], v[12:13], v[32:33], v[56:57]
	v_and_b32_e32 v67, 0xffff0000, v62
	v_lshlrev_b32_e32 v66, 16, v62
	v_and_b32_e32 v61, 0xffff0000, v63
	v_lshlrev_b32_e32 v60, 16, v63
	global_store_dwordx2 v[42:43], v[16:17], off
	v_cvt_pk_bf16_f32 v16, v14, v15
	s_waitcnt vmcnt(16)
	v_pk_fma_f32 v[14:15], v[14:15], v[34:35], v[64:65]
	v_cvt_pk_bf16_f32 v17, v12, v13
	v_pk_fma_f32 v[12:13], v[12:13], v[36:37], v[58:59]
	global_store_dwordx2 v[48:49], v[18:19], off
	v_cvt_pk_bf16_f32 v18, v14, v15
	s_waitcnt vmcnt(16)
	v_pk_fma_f32 v[14:15], v[14:15], v[38:39], v[66:67]
	v_cvt_pk_bf16_f32 v19, v12, v13
	v_pk_fma_f32 v[12:13], v[12:13], v[40:41], v[60:61]
	global_store_dwordx2 v[50:51], v[16:17], off
	global_store_dwordx2 v[52:53], v[18:19], off
	v_cvt_pk_bf16_f32 v148, v14, v15
	v_cvt_pk_bf16_f32 v149, v12, v13
	global_store_dwordx2 v[100:101], v[148:149], off
	s_waitcnt vmcnt(12)
	v_lshlrev_b32_e32 v100, 16, v128
	v_and_b32_e32 v101, 0xffff0000, v128
	v_lshlrev_b32_e32 v128, 16, v129
	v_and_b32_e32 v129, 0xffff0000, v129
	s_waitcnt vmcnt(11)
	v_pk_fma_f32 v[14:15], v[14:15], v[102:103], v[100:101]
	v_pk_fma_f32 v[12:13], v[12:13], v[104:105], v[128:129]
	v_cvt_pk_bf16_f32 v104, v14, v15
	v_cvt_pk_bf16_f32 v105, v12, v13
	global_store_dwordx2 v[130:131], v[104:105], off
	s_waitcnt vmcnt(11)
	v_lshlrev_b32_e32 v100, 16, v138
	v_and_b32_e32 v101, 0xffff0000, v138
	v_lshlrev_b32_e32 v102, 16, v139
	v_and_b32_e32 v103, 0xffff0000, v139
	s_waitcnt vmcnt(10)
	v_and_b32_e32 v129, 0xffff0000, v140
	v_lshlrev_b32_e32 v128, 16, v140
	v_and_b32_e32 v153, 0xffff0000, v141
	v_lshlrev_b32_e32 v152, 16, v141
	s_waitcnt vmcnt(6)
	v_pk_fma_f32 v[14:15], v[14:15], v[106:107], v[100:101]
	v_pk_fma_f32 v[12:13], v[12:13], v[108:109], v[102:103]
	v_and_b32_e32 v139, 0xffff0000, v142
	v_lshlrev_b32_e32 v138, 16, v142
	v_and_b32_e32 v141, 0xffff0000, v143
	v_lshlrev_b32_e32 v140, 16, v143
	v_cvt_pk_bf16_f32 v100, v14, v15
	s_waitcnt vmcnt(5)
	v_pk_fma_f32 v[14:15], v[14:15], v[110:111], v[128:129]
	v_cvt_pk_bf16_f32 v101, v12, v13
	v_pk_fma_f32 v[12:13], v[12:13], v[112:113], v[152:153]
	v_and_b32_e32 v149, 0xffff0000, v144
	v_lshlrev_b32_e32 v148, 16, v144
	v_and_b32_e32 v143, 0xffff0000, v145
	v_lshlrev_b32_e32 v142, 16, v145
	v_cvt_pk_bf16_f32 v102, v14, v15
	s_waitcnt vmcnt(4)
	v_pk_fma_f32 v[14:15], v[14:15], v[114:115], v[138:139]
	v_cvt_pk_bf16_f32 v103, v12, v13
	v_pk_fma_f32 v[12:13], v[12:13], v[116:117], v[140:141]
	v_and_b32_e32 v151, 0xffff0000, v146
	v_lshlrev_b32_e32 v150, 16, v146
	v_and_b32_e32 v145, 0xffff0000, v147
	v_lshlrev_b32_e32 v144, 16, v147
	global_store_dwordx2 v[126:127], v[100:101], off
	v_cvt_pk_bf16_f32 v100, v14, v15
	s_waitcnt vmcnt(4)
	v_pk_fma_f32 v[14:15], v[14:15], v[118:119], v[148:149]
	v_cvt_pk_bf16_f32 v101, v12, v13
	v_pk_fma_f32 v[12:13], v[12:13], v[120:121], v[142:143]
	global_store_dwordx2 v[132:133], v[102:103], off
	v_cvt_pk_bf16_f32 v102, v14, v15
	s_waitcnt vmcnt(4)
	v_pk_fma_f32 v[14:15], v[14:15], v[122:123], v[150:151]
	v_cvt_pk_bf16_f32 v103, v12, v13
	v_pk_fma_f32 v[12:13], v[12:13], v[124:125], v[144:145]
	global_store_dwordx2 v[134:135], v[100:101], off
	global_store_dwordx2 v[136:137], v[102:103], off
	s_mov_b64 s[0:1], 0
